# combined: v6 + G1 epilogue fast path + P2 empty-queue probe + attention near-tile bias read batching
# speedup vs baseline: 1.0121x; 1.0073x over previous
.LBB0_527:
	v_mfma_f32_16x16x32_bf16 v[126:129], v[122:125], v[50:53], 0
	s_cmp_lt_u32 s20, 12
	s_cselect_b64 s[2:3], -1, 0
	s_cmp_gt_u32 s20, 11
	v_mfma_f32_16x16x32_bf16 v[142:145], v[118:121], v[54:57], v[126:129]
	s_cselect_b64 s[14:15], -1, 0
	s_add_i32 s4, s18, 0x20400
	v_mov_b32_e32 v1, s4
	v_mfma_f32_16x16x32_bf16 v[126:129], v[122:125], v[58:61], 0
	ds_read_b32 v210, v1
	s_and_b64 vcc, exec, s[2:3]
	v_mfma_f32_16x16x32_bf16 v[134:137], v[118:121], v[62:65], v[126:129]
	v_mfma_f32_16x16x32_bf16 v[126:129], v[122:125], v[66:69], 0
	v_mfma_f32_16x16x32_bf16 v[122:125], v[122:125], v[74:77], 0
	v_mfma_f32_16x16x32_bf16 v[126:129], v[118:121], v[70:73], v[126:129]
	v_mfma_f32_16x16x32_bf16 v[118:121], v[118:121], v[78:81], v[122:125]
	v_mfma_f32_16x16x32_bf16 v[122:125], v[146:149], v[50:53], 0
	v_mfma_f32_16x16x32_bf16 v[138:141], v[114:117], v[54:57], v[122:125]
	v_mfma_f32_16x16x32_bf16 v[122:125], v[146:149], v[58:61], 0
	v_mfma_f32_16x16x32_bf16 v[130:133], v[114:117], v[62:65], v[122:125]
	v_mfma_f32_16x16x32_bf16 v[122:125], v[146:149], v[66:69], 0
	v_mfma_f32_16x16x32_bf16 v[146:149], v[146:149], v[74:77], 0
	v_mfma_f32_16x16x32_bf16 v[122:125], v[114:117], v[70:73], v[122:125]
	v_mfma_f32_16x16x32_bf16 v[114:117], v[114:117], v[78:81], v[146:149]
	s_cbranch_vccnz .LBB0_529
	s_nop 4
	ds_read2_b32 v[214:215], v205 offset0:66 offset1:67
	ds_read2_b32 v[216:217], v205 offset0:64 offset1:65
	ds_read2_b32 v[218:219], v205 offset0:2 offset1:3
	ds_read2_b32 v[220:221], v205 offset1:1
	ds_read2_b32 v[222:223], v205 offset0:18 offset1:19
	ds_read2_b32 v[224:225], v205 offset0:16 offset1:17
	ds_read2_b32 v[226:227], v205 offset0:34 offset1:35
	ds_read2_b32 v[228:229], v205 offset0:32 offset1:33
	ds_read2_b32 v[230:231], v205 offset0:50 offset1:51
	ds_read2_b32 v[232:233], v205 offset0:48 offset1:49
	s_waitcnt lgkmcnt(8)
	v_pk_fma_f32 v[118:119], v[118:119], s[88:89], v[214:215] op_sel:[0,0,1] op_sel_hi:[1,0,0]
	v_pk_fma_f32 v[120:121], v[120:121], s[88:89], v[216:217] op_sel:[0,0,1] op_sel_hi:[1,0,0]
	s_waitcnt lgkmcnt(6)
	v_pk_fma_f32 v[138:139], v[138:139], s[88:89], v[218:219] op_sel:[0,0,1] op_sel_hi:[1,0,0]
	v_pk_fma_f32 v[140:141], v[140:141], s[88:89], v[220:221] op_sel:[0,0,1] op_sel_hi:[1,0,0]
	s_waitcnt lgkmcnt(5)
	v_pk_fma_f32 v[142:143], v[142:143], s[88:89], v[222:223] op_sel:[0,0,1] op_sel_hi:[1,0,0]
	v_pk_fma_f32 v[130:131], v[130:131], s[88:89], v[222:223] op_sel:[0,0,1] op_sel_hi:[1,0,0]
	s_waitcnt lgkmcnt(4)
	v_pk_fma_f32 v[144:145], v[144:145], s[88:89], v[224:225] op_sel:[0,0,1] op_sel_hi:[1,0,0]
	v_pk_fma_f32 v[132:133], v[132:133], s[88:89], v[224:225] op_sel:[0,0,1] op_sel_hi:[1,0,0]
	s_waitcnt lgkmcnt(3)
	v_pk_fma_f32 v[134:135], v[134:135], s[88:89], v[226:227] op_sel:[0,0,1] op_sel_hi:[1,0,0]
	v_pk_fma_f32 v[122:123], v[122:123], s[88:89], v[226:227] op_sel:[0,0,1] op_sel_hi:[1,0,0]
	s_waitcnt lgkmcnt(2)
	v_pk_fma_f32 v[136:137], v[136:137], s[88:89], v[228:229] op_sel:[0,0,1] op_sel_hi:[1,0,0]
	v_pk_fma_f32 v[124:125], v[124:125], s[88:89], v[228:229] op_sel:[0,0,1] op_sel_hi:[1,0,0]
	s_waitcnt lgkmcnt(1)
	v_pk_fma_f32 v[126:127], v[126:127], s[88:89], v[230:231] op_sel:[0,0,1] op_sel_hi:[1,0,0]
	v_pk_fma_f32 v[114:115], v[114:115], s[88:89], v[230:231] op_sel:[0,0,1] op_sel_hi:[1,0,0]
	s_waitcnt lgkmcnt(0)
	v_pk_fma_f32 v[128:129], v[128:129], s[88:89], v[232:233] op_sel:[0,0,1] op_sel_hi:[1,0,0]
	v_pk_fma_f32 v[116:117], v[116:117], s[88:89], v[232:233] op_sel:[0,0,1] op_sel_hi:[1,0,0]
